# rs_fill: reuse rsqrt table values when consecutive units share the row block (WIN, FFI) on top of v6
# speedup vs baseline: 1.0539x; 1.0060x over previous
; #define LAS __attribute__((address_space(3)))
; __device__ __forceinline__ int ltid() { int t = threadIdx.x; asm volatile("" : "+v"(t)); return t; }
; template <int PH, int SUB> __device__ __forceinline__ void rs_fill(LAS unsigned char* lds, const Epi& E) {
;     constexpr int kind = shape_of<PH, SUB>().kind;
;     if constexpr ((kind == K_WIN || kind == K_MG_G || kind == K_FFI || kind == K_PLE) && !(PH == PH_MERGE && SUB != 0)) {
;         const int tidx = ltid();
;         const float* ssq = (const float*)(E.ws + OFF_SSQ + (kind == K_FFI ? SSQ_BYTES : (kind == K_PLE ? 2 * SSQ_BYTES : 0)));
;         LAS float* tab = (LAS float*)(lds + STAGE_BYTES + 16);
;         for (int i = 0; i < 12; ++i) { Unit u; if (!sched_next<PH, SUB>(E.ws, E.layer, i, u)) break;
;             const int r = tidx >> 1, hf = tidx & 1; const size_t row = (size_t)(u.pm * 256 + r); f32x4 a, b;
.LBB0_194:
	v_readlane_b32 s2, v233, 5
	v_readlane_b32 s3, v233, 6
	s_load_dwordx4 s[8:11], s[2:3], 0xc8
	v_mov_b32_e32 v0, v186
	v_readlane_b32 s4, v231, 56
	v_and_b32_e32 v9, 1, v0
	v_ashrrev_i32_e32 v8, 1, v0
	s_waitcnt lgkmcnt(0)
	s_add_u32 s2, s10, 0xa800000
	v_lshlrev_b32_e32 v0, 16, v9
	s_addc_u32 s3, s11, 0
	v_or_b32_e32 v2, 0x8000, v0
	v_mov_b32_e32 v3, v1
	v_cmp_eq_u32_e64 s[6:7], 0, v9
	v_lshl_add_u32 v9, v8, 2, s4
	s_movk_i32 s14, 0xd000
	s_mov_b32 s100, -1
	s_mov_b32 s15, s72
	s_branch .LBB0_197

; template <int PH, int SUB> __device__ __forceinline__ void rs_fill(LAS unsigned char* lds, const Epi& E) {
;     ...
;         for (int i = 0; i < 12; ++i) { Unit u; if (!sched_next<PH, SUB>(E.ws, E.layer, i, u)) break;
;             const int r = tidx >> 1, hf = tidx & 1; const size_t row = (size_t)(u.pm * 256 + r); f32x4 a, b;
;             { unsigned* pa = (unsigned*)(ssq + ((size_t)(2 * hf) * T_TOK + row) * 4); unsigned* pb = (unsigned*)(ssq + ((size_t)(2 * hf + 1) * T_TOK + row) * 4);
; #pragma unroll
;               for (int j = 0; j < 4; ++j) { a[j] = __uint_as_float(__hip_atomic_load(pa + j, __ATOMIC_RELAXED, __HIP_MEMORY_SCOPE_AGENT)); b[j] = __uint_as_float(__hip_atomic_load(pb + j, __ATOMIC_RELAXED, __HIP_MEMORY_SCOPE_AGENT)); } }
;             float t = ((a[0] + a[1]) + (a[2] + a[3])) + ((b[0] + b[1]) + (b[2] + b[3])); t += __shfl_xor(t, 1);
;             if (hf == 0) tab[u.ord * 256 + r] = rsqrtf(t * (1.0f / 1024.0f) + 1e-6f); }
.LBB0_197:
	s_cmpk_gt_i32 s15, 0x57f
	s_mov_b64 s[12:13], -1
	s_cbranch_scc1 .LBB0_196
	s_ashr_i32 s4, s15, 31
	s_lshr_b32 s4, s4, 29
	s_add_i32 s4, s15, s4
	s_ashr_i32 s5, s4, 3
	s_and_b32 s4, s4, -8
	s_sub_i32 s4, s15, s4
	s_lshr_b32 s12, s4, 31
	s_or_b32 s12, s12, 0xb0
	s_mul_i32 s4, s12, s4
	s_add_i32 s4, s4, s5
	s_mul_hi_i32 s5, s4, 0x2e8ba2e9
	s_lshr_b32 s12, s5, 31
	s_ashr_i32 s5, s5, 4
	s_add_i32 s5, s5, s12
	s_lshl_b32 s16, s5, 3
	s_sub_i32 s12, 0x80, s16
	s_min_u32 s17, s12, 8
	s_mulk_i32 s5, 0x58
	s_sub_i32 s4, s4, s5
	s_waitcnt lgkmcnt(0)
	v_cvt_f32_ubyte0_e32 v11, s17
	v_cvt_f32_i32_e32 v10, s4
	v_rcp_iflag_f32_e32 v12, v11
	s_ashr_i32 s5, s4, 30
	s_or_b32 s5, s5, 1
	v_cmp_lt_i32_e32 vcc, v191, v192
	v_mul_f32_e32 v12, v10, v12
	v_trunc_f32_e32 v12, v12
	v_fma_f32 v10, -v12, v11, v10
	v_cvt_i32_f32_e32 v12, v12
	v_cmp_ge_f32_e64 s[12:13], |v10|, v11
	s_and_b64 s[12:13], s[12:13], exec
	s_cselect_b32 s5, s5, 0
	v_readfirstlane_b32 s12, v12
	s_add_i32 s5, s12, s5
	s_mul_i32 s5, s5, s17
	s_sub_i32 s4, s4, s5
	s_sext_i32_i8 s4, s4
	s_add_i32 s16, s16, s4
	s_cmp_eq_u32 s16, s100
	s_cbranch_scc1 .Lrsf_win_reuse
	s_mov_b32 s100, s16
	v_lshl_add_u32 v10, s16, 8, v8
	v_ashrrev_i32_e32 v11, 31, v10
	v_lshl_add_u64 v[12:13], v[10:11], 0, v[0:1]
	v_lshl_add_u64 v[10:11], v[10:11], 0, v[2:3]
	v_lshl_add_u64 v[12:13], v[12:13], 4, s[2:3]
	v_lshl_add_u64 v[10:11], v[10:11], 4, s[2:3]
	global_load_dword v14, v[12:13], off sc1
	global_load_dword v15, v[10:11], off sc1
	global_load_dword v16, v[12:13], off offset:4 sc1
	global_load_dword v17, v[10:11], off offset:4 sc1
	global_load_dword v18, v[12:13], off offset:8 sc1
	global_load_dword v19, v[10:11], off offset:8 sc1
	s_nop 0
	global_load_dword v12, v[12:13], off offset:12 sc1
	s_nop 0
	global_load_dword v10, v[10:11], off offset:12 sc1
	v_cndmask_b32_e32 v11, v190, v191, vcc
	v_lshlrev_b32_e32 v11, 2, v11
	s_waitcnt vmcnt(5)
	v_add_f32_e32 v13, v14, v16
	s_waitcnt vmcnt(4)
	v_add_f32_e32 v14, v15, v17
	s_waitcnt vmcnt(1)
	v_add_f32_e32 v12, v18, v12
	s_waitcnt vmcnt(0)
	v_add_f32_e32 v10, v19, v10
	v_add_f32_e32 v12, v13, v12
	v_add_f32_e32 v10, v14, v10
	v_add_f32_e32 v10, v12, v10
	ds_bpermute_b32 v11, v11, v10
	s_and_saveexec_b64 s[12:13], s[6:7]
	s_cbranch_execz .LBB0_195
	s_waitcnt lgkmcnt(0)
	v_add_f32_e32 v10, v10, v11
	v_fmamk_f32 v10, v10, 0x3a800000, v188
	v_mul_f32_e32 v11, 0x4b800000, v10
	v_cmp_gt_f32_e32 vcc, s90, v10
	s_nop 1
	v_cndmask_b32_e32 v10, v10, v11, vcc
	v_rsq_f32_e32 v10, v10
	s_nop 0
	v_mul_f32_e32 v11, 0x45800000, v10
	v_cndmask_b32_e32 v10, v10, v11, vcc
	v_add_u32_e32 v11, s14, v9
	v_mov_b32_e32 v20, v10
	ds_write_b32 v11, v10 offset:12288
	s_branch .LBB0_195
.Lrsf_win_reuse:
	s_and_saveexec_b64 s[12:13], s[6:7]
	v_add_u32_e32 v11, s14, v9
	ds_write_b32 v11, v20 offset:12288
	s_branch .LBB0_195

; #define LAS __attribute__((address_space(3)))
; __device__ __forceinline__ int ltid() { int t = threadIdx.x; asm volatile("" : "+v"(t)); return t; }
; template <int PH, int SUB> __device__ __forceinline__ void rs_fill(LAS unsigned char* lds, const Epi& E) {
;     constexpr int kind = shape_of<PH, SUB>().kind;
;     if constexpr ((kind == K_WIN || kind == K_MG_G || kind == K_FFI || kind == K_PLE) && !(PH == PH_MERGE && SUB != 0)) {
;         const int tidx = ltid();
;         const float* ssq = (const float*)(E.ws + OFF_SSQ + (kind == K_FFI ? SSQ_BYTES : (kind == K_PLE ? 2 * SSQ_BYTES : 0)));
;         LAS float* tab = (LAS float*)(lds + STAGE_BYTES + 16);
;         for (int i = 0; i < 12; ++i) { Unit u; if (!sched_next<PH, SUB>(E.ws, E.layer, i, u)) break;
;             const int r = tidx >> 1, hf = tidx & 1; const size_t row = (size_t)(u.pm * 256 + r); f32x4 a, b;
.LBB0_1105:
	s_or_b64 exec, exec, s[2:3]
	v_readlane_b32 s2, v233, 5
	v_readlane_b32 s3, v233, 6
	s_waitcnt lgkmcnt(0)
	s_barrier
	s_load_dwordx2 s[2:3], s[2:3], 0xd0
	v_mov_b32_e32 v0, v186
	v_readlane_b32 s4, v231, 56
	v_and_b32_e32 v9, 1, v0
	s_waitcnt lgkmcnt(0)
	s_add_u32 s8, s2, 0xaa00000
	v_ashrrev_i32_e32 v8, 1, v0
	v_lshlrev_b32_e32 v0, 16, v9
	s_addc_u32 s9, s3, 0
	v_or_b32_e32 v2, 0x8000, v0
	v_mov_b32_e32 v3, v1
	v_cmp_eq_u32_e64 s[6:7], 0, v9
	v_lshl_add_u32 v9, v8, 2, s4
	s_movk_i32 s12, 0xd000
	s_mov_b32 s100, -1
	s_mov_b32 s13, s72
	s_branch .LBB0_1108

; template <int PH, int SUB> __device__ __forceinline__ void rs_fill(LAS unsigned char* lds, const Epi& E) {
;     ...
;         for (int i = 0; i < 12; ++i) { Unit u; if (!sched_next<PH, SUB>(E.ws, E.layer, i, u)) break;
;             const int r = tidx >> 1, hf = tidx & 1; const size_t row = (size_t)(u.pm * 256 + r); f32x4 a, b;
;             { unsigned* pa = (unsigned*)(ssq + ((size_t)(2 * hf) * T_TOK + row) * 4); unsigned* pb = (unsigned*)(ssq + ((size_t)(2 * hf + 1) * T_TOK + row) * 4);
; #pragma unroll
;               for (int j = 0; j < 4; ++j) { a[j] = __uint_as_float(__hip_atomic_load(pa + j, __ATOMIC_RELAXED, __HIP_MEMORY_SCOPE_AGENT)); b[j] = __uint_as_float(__hip_atomic_load(pb + j, __ATOMIC_RELAXED, __HIP_MEMORY_SCOPE_AGENT)); } }
;             float t = ((a[0] + a[1]) + (a[2] + a[3])) + ((b[0] + b[1]) + (b[2] + b[3])); t += __shfl_xor(t, 1);
;             if (hf == 0) tab[u.ord * 256 + r] = rsqrtf(t * (1.0f / 1024.0f) + 1e-6f); }
.LBB0_1108:
	s_cmpk_gt_i32 s13, 0xaff
	s_mov_b64 s[10:11], -1
	s_cbranch_scc1 .LBB0_1107
	s_ashr_i32 s4, s13, 31
	s_lshr_b32 s4, s4, 29
	s_add_i32 s4, s13, s4
	s_ashr_i32 s5, s4, 3
	s_and_b32 s4, s4, -8
	s_sub_i32 s4, s13, s4
	s_lshr_b32 s10, s4, 31
	s_or_b32 s10, s10, 0x160
	s_mul_i32 s4, s10, s4
	s_add_i32 s4, s4, s5
	s_mul_hi_i32 s5, s4, 0x2e8ba2e9
	s_lshr_b32 s10, s5, 31
	s_ashr_i32 s5, s5, 5
	s_add_i32 s5, s5, s10
	s_lshl_b32 s10, s5, 3
	s_sub_i32 s11, 0x80, s10
	s_min_u32 s11, s11, 8
	s_mulk_i32 s5, 0xb0
	s_sub_i32 s14, s4, s5
	s_waitcnt lgkmcnt(0)
	v_cvt_f32_ubyte0_e32 v11, s11
	v_cvt_f32_i32_e32 v10, s14
	v_rcp_iflag_f32_e32 v12, v11
	s_ashr_i32 s4, s14, 30
	s_or_b32 s15, s4, 1
	v_cmp_lt_i32_e32 vcc, v191, v192
	v_mul_f32_e32 v12, v10, v12
	v_trunc_f32_e32 v12, v12
	v_fma_f32 v10, -v12, v11, v10
	v_cvt_i32_f32_e32 v12, v12
	v_cmp_ge_f32_e64 s[4:5], |v10|, v11
	s_and_b64 s[4:5], s[4:5], exec
	s_cselect_b32 s4, s15, 0
	v_readfirstlane_b32 s5, v12
	s_add_i32 s4, s5, s4
	s_mul_i32 s4, s4, s11
	s_sub_i32 s4, s14, s4
	s_sext_i32_i16 s4, s4
	s_add_i32 s10, s10, s4
	s_cmp_eq_u32 s10, s100
	s_cbranch_scc1 .Lrsf_ffi_reuse
	s_mov_b32 s100, s10
	v_lshl_add_u32 v10, s10, 8, v8
	v_ashrrev_i32_e32 v11, 31, v10
	v_lshl_add_u64 v[12:13], v[10:11], 0, v[0:1]
	v_lshl_add_u64 v[10:11], v[10:11], 0, v[2:3]
	v_lshl_add_u64 v[12:13], v[12:13], 4, s[8:9]
	v_lshl_add_u64 v[10:11], v[10:11], 4, s[8:9]
	global_load_dword v14, v[12:13], off sc1
	global_load_dword v15, v[10:11], off sc1
	global_load_dword v16, v[12:13], off offset:4 sc1
	global_load_dword v17, v[10:11], off offset:4 sc1
	global_load_dword v18, v[12:13], off offset:8 sc1
	global_load_dword v19, v[10:11], off offset:8 sc1
	s_nop 0
	global_load_dword v12, v[12:13], off offset:12 sc1
	s_nop 0
	global_load_dword v10, v[10:11], off offset:12 sc1
	v_cndmask_b32_e32 v11, v190, v191, vcc
	v_lshlrev_b32_e32 v11, 2, v11
	s_waitcnt vmcnt(5)
	v_add_f32_e32 v13, v14, v16
	s_waitcnt vmcnt(4)
	v_add_f32_e32 v14, v15, v17
	s_waitcnt vmcnt(1)
	v_add_f32_e32 v12, v18, v12
	s_waitcnt vmcnt(0)
	v_add_f32_e32 v10, v19, v10
	v_add_f32_e32 v12, v13, v12
	v_add_f32_e32 v10, v14, v10
	v_add_f32_e32 v10, v12, v10
	ds_bpermute_b32 v11, v11, v10
	s_and_saveexec_b64 s[10:11], s[6:7]
	s_cbranch_execz .LBB0_1106
	s_waitcnt lgkmcnt(0)
	v_add_f32_e32 v10, v10, v11
	v_fmamk_f32 v10, v10, 0x3a800000, v188
	v_mul_f32_e32 v11, 0x4b800000, v10
	v_cmp_gt_f32_e32 vcc, s90, v10
	s_nop 1
	v_cndmask_b32_e32 v10, v10, v11, vcc
	v_rsq_f32_e32 v10, v10
	s_nop 0
	v_mul_f32_e32 v11, 0x45800000, v10
	v_cndmask_b32_e32 v10, v10, v11, vcc
	v_add_u32_e32 v11, s12, v9
	v_mov_b32_e32 v20, v10
	ds_write_b32 v11, v10 offset:12288
	s_branch .LBB0_1106
.Lrsf_ffi_reuse:
	s_and_saveexec_b64 s[10:11], s[6:7]
	v_add_u32_e32 v11, s12, v9
	ds_write_b32 v11, v20 offset:12288
	s_branch .LBB0_1106

; #define LAS __attribute__((address_space(3)))
; __global__ void __launch_bounds__(512) fwd_megakernel(Params Parg) {
;     ...
;     cg::grid_group grid = cg::this_grid();
;     extern __shared__ __attribute__((aligned(16))) unsigned char smem[];
;     LAS unsigned char* lds = (LAS unsigned char*)smem;
	.amdhsa_kernel _Z14fwd_megakernel6Params
		.amdhsa_group_segment_fixed_size 0
		.amdhsa_private_segment_fixed_size 0
		.amdhsa_kernarg_size 472
		.amdhsa_user_sgpr_count 2
		.amdhsa_user_sgpr_dispatch_ptr 0
		.amdhsa_user_sgpr_queue_ptr 0
		.amdhsa_user_sgpr_kernarg_segment_ptr 1
		.amdhsa_user_sgpr_dispatch_id 0
		.amdhsa_user_sgpr_kernarg_preload_length 0
		.amdhsa_user_sgpr_kernarg_preload_offset 0
		.amdhsa_user_sgpr_private_segment_size 0
		.amdhsa_uses_dynamic_stack 0
		.amdhsa_enable_private_segment 0
		.amdhsa_system_sgpr_workgroup_id_x 1
		.amdhsa_system_sgpr_workgroup_id_y 0
		.amdhsa_system_sgpr_workgroup_id_z 0
		.amdhsa_system_sgpr_workgroup_info 0
		.amdhsa_system_vgpr_workitem_id 2
		.amdhsa_next_free_vgpr 256
		.amdhsa_next_free_sgpr 102
		.amdhsa_accum_offset 256
		.amdhsa_reserve_vcc 1
		.amdhsa_float_round_mode_32 0
		.amdhsa_float_round_mode_16_64 0
		.amdhsa_float_denorm_mode_32 3
		.amdhsa_float_denorm_mode_16_64 3
		.amdhsa_dx10_clamp 1
		.amdhsa_ieee_mode 1
		.amdhsa_fp16_overflow 0
		.amdhsa_tg_split 0
		.amdhsa_exception_fp_ieee_invalid_op 0
		.amdhsa_exception_fp_denorm_src 0
		.amdhsa_exception_fp_ieee_div_zero 0
		.amdhsa_exception_fp_ieee_overflow 0
		.amdhsa_exception_fp_ieee_underflow 0
		.amdhsa_exception_fp_ieee_inexact 0
		.amdhsa_exception_int_div_zero 0
	.end_amdhsa_kernel

; #define LAS __attribute__((address_space(3)))
; __global__ void __launch_bounds__(512) fwd_megakernel(Params Parg) {
;     ...
;     cg::grid_group grid = cg::this_grid();
;     extern __shared__ __attribute__((aligned(16))) unsigned char smem[];
;     LAS unsigned char* lds = (LAS unsigned char*)smem;
amdhsa.kernels:
  - .agpr_count:     0
    .args:
      - .offset:         0
        .size:           216
        .value_kind:     by_value
      - .offset:         216
        .size:           4
        .value_kind:     hidden_block_count_x
      - .offset:         220
        .size:           4
        .value_kind:     hidden_block_count_y
      - .offset:         224
        .size:           4
        .value_kind:     hidden_block_count_z
      - .offset:         228
        .size:           2
        .value_kind:     hidden_group_size_x
      - .offset:         230
        .size:           2
        .value_kind:     hidden_group_size_y
      - .offset:         232
        .size:           2
        .value_kind:     hidden_group_size_z
      - .offset:         234
        .size:           2
        .value_kind:     hidden_remainder_x
      - .offset:         236
        .size:           2
        .value_kind:     hidden_remainder_y
      - .offset:         238
        .size:           2
        .value_kind:     hidden_remainder_z
      - .offset:         256
        .size:           8
        .value_kind:     hidden_global_offset_x
      - .offset:         264
        .size:           8
        .value_kind:     hidden_global_offset_y
      - .offset:         272
        .size:           8
        .value_kind:     hidden_global_offset_z
      - .offset:         280
        .size:           2
        .value_kind:     hidden_grid_dims
      - .offset:         304
        .size:           8
        .value_kind:     hidden_multigrid_sync_arg
      - .offset:         336
        .size:           4
        .value_kind:     hidden_dynamic_lds_size
    .group_segment_fixed_size: 0
    .kernarg_segment_align: 8
    .kernarg_segment_size: 472
    .language:       OpenCL C
    .language_version:
      - 2
      - 0
    .max_flat_workgroup_size: 512
    .name:           _Z14fwd_megakernel6Params
    .private_segment_fixed_size: 0
    .sgpr_count:     108
    .sgpr_spill_count: 328
    .symbol:         _Z14fwd_megakernel6Params.kd
    .uniform_work_group_size: 1
    .uses_dynamic_stack: false
    .vgpr_count:     256
    .vgpr_spill_count: 0
    .wavefront_size: 64
